# P0 scaled transposes (w_uq, w_ukv): batch of non-binding loads touches the 16 weight addresses before each serial pass (on v66)
# speedup vs baseline: 1.0224x; 1.0011x over previous
; #define LAS __attribute__((address_space(3)))
; __device__ __forceinline__ void tr_item(const float* W, int K, int N, bf16_t* WT, int ldt, int rowmode, const float* ksc, LAS float* scr, int item, int lane) {
;     const int nblk = N / 32, kb = item / nblk, nb = item % nblk, k0 = 64 * kb, n0 = 32 * nb;
; #pragma unroll 16
;     for (int i = 0; i < 32; ++i) { const int kk = 2 * i + (lane >> 5); float v = W[(size_t)(k0 + kk) * N + n0 + (lane & 31)]; if (ksc) v *= ksc[k0 + kk]; scr[kk * 33 + (lane & 31)] = v; }
.LBB0_50:
	v_lshl_add_u64 v[118:119], v[38:39], 0, s[18:19]
	global_load_dword v100, v[118:119], off
	v_lshl_add_u64 v[118:119], v[34:35], 0, s[18:19]
	global_load_dword v101, v[118:119], off
	v_lshl_add_u64 v[118:119], v[32:33], 0, s[18:19]
	global_load_dword v102, v[118:119], off
	v_lshl_add_u64 v[118:119], v[30:31], 0, s[18:19]
	global_load_dword v103, v[118:119], off
	v_lshl_add_u64 v[118:119], v[28:29], 0, s[18:19]
	global_load_dword v104, v[118:119], off
	v_lshl_add_u64 v[118:119], v[26:27], 0, s[18:19]
	global_load_dword v105, v[118:119], off
	v_lshl_add_u64 v[118:119], v[24:25], 0, s[18:19]
	global_load_dword v106, v[118:119], off
	v_lshl_add_u64 v[118:119], v[22:23], 0, s[18:19]
	global_load_dword v107, v[118:119], off
	v_lshl_add_u64 v[118:119], v[20:21], 0, s[18:19]
	global_load_dword v108, v[118:119], off
	v_lshl_add_u64 v[118:119], v[18:19], 0, s[18:19]
	global_load_dword v109, v[118:119], off
	v_lshl_add_u64 v[118:119], v[16:17], 0, s[18:19]
	global_load_dword v110, v[118:119], off
	v_lshl_add_u64 v[118:119], v[14:15], 0, s[18:19]
	global_load_dword v111, v[118:119], off
	v_lshl_add_u64 v[118:119], v[12:13], 0, s[18:19]
	global_load_dword v112, v[118:119], off
	v_lshl_add_u64 v[118:119], v[10:11], 0, s[18:19]
	global_load_dword v113, v[118:119], off
	v_lshl_add_u64 v[118:119], v[8:9], 0, s[18:19]
	global_load_dword v114, v[118:119], off
	v_lshl_add_u64 v[118:119], v[4:5], 0, s[18:19]
	global_load_dword v115, v[118:119], off
	v_lshl_add_u64 v[40:41], v[38:39], 0, s[18:19]
	flat_load_dword v2, v[40:41]
	v_cndmask_b32_e64 v40, 0, 1, s[20:21]
	v_cmp_ne_u32_e64 s[4:5], 1, v40
	s_andn2_b64 vcc, exec, s[20:21]
	s_cbranch_vccnz .LBB0_52
	v_lshl_add_u64 v[40:41], s[8:9], 0, v[36:37]
	flat_load_dword v40, v[40:41]
	s_waitcnt vmcnt(0) lgkmcnt(0)
	v_mul_f32_e32 v2, v2, v40
